# FF2 K-loops: the two A-operand LDS-DMA pieces of the 6-piece sub-phase issued first (right after the barrier), B pieces after
# speedup vs baseline: 1.0037x; 1.0037x over previous
.LBB0_33:
	s_add_i32 s63, 0, 0x10000
	s_add_i32 s64, 0, 0x14000
	v_add_u32_e32 v64, s63, v78
	ds_read_b128 v[138:141], v64
	ds_read_b128 v[142:145], v64 offset:1024
	ds_read_b128 v[146:149], v64 offset:2048
	ds_read_b128 v[150:153], v64 offset:3072
	v_add_u32_e32 v64, s64, v78
	ds_read_b128 v[154:157], v64
	ds_read_b128 v[158:161], v64 offset:1024
	ds_read_b128 v[162:165], v64 offset:2048
	ds_read_b128 v[166:169], v64 offset:3072
	s_add_u32 s60, s56, s92
	s_addc_u32 s61, s57, s93
	s_add_u32 s2, s60, 0x2500100
	s_addc_u32 s3, s61, 0
	s_add_u32 s54, s58, s92
	s_addc_u32 s55, s59, s93
	s_cmpk_eq_i32 s92, 0x1f00
	s_cselect_b32 s3, s47, s3
	s_cselect_b32 s2, s46, s2
	s_cselect_b32 s55, s41, s55
	s_cselect_b32 s54, s40, s54
	v_mov_b32_e32 v64, v74
	ds_read_b128 v[170:173], v79
	ds_read_b128 v[174:177], v79 offset:1024
	ds_read_b128 v[178:181], v79 offset:2048
	ds_read_b128 v[182:185], v79 offset:3072
	ds_read_b128 v[190:193], v79 offset:4096
	ds_read_b128 v[194:197], v79 offset:5120
	ds_read_b128 v[198:201], v79 offset:6144
	ds_read_b128 v[214:217], v79 offset:7168
	s_add_i32 m0, s17, 0xc000
	v_lshl_add_u64 v[80:81], s[60:61], 0, v[64:65]
	v_lshl_add_u64 v[80:81], v[80:81], 0, s[66:67]
	v_mov_b32_e32 v64, v76
	global_load_lds_dwordx4 v[80:81], off
	s_add_i32 m0, s17, 0xe000
	v_lshl_add_u64 v[80:81], s[60:61], 0, v[64:65]
	v_lshl_add_u64 v[80:81], v[80:81], 0, s[66:67]
	global_load_lds_dwordx4 v[80:81], off
	s_waitcnt vmcnt(8)
	s_waitcnt lgkmcnt(0)
	s_barrier
	s_setprio 1
	s_waitcnt lgkmcnt(0)
	v_mfma_f32_16x16x32_bf16 v[70:73], v[138:141], v[170:173], v[70:73]
	v_mfma_f32_16x16x32_bf16 v[56:59], v[146:149], v[170:173], v[56:59]
	v_mfma_f32_16x16x32_bf16 v[126:129], v[138:141], v[178:181], v[126:129]
	v_mfma_f32_16x16x32_bf16 v[122:125], v[146:149], v[178:181], v[122:125]
	v_mfma_f32_16x16x32_bf16 v[110:113], v[138:141], v[190:193], v[110:113]
	v_mfma_f32_16x16x32_bf16 v[106:109], v[146:149], v[190:193], v[106:109]
	v_mfma_f32_16x16x32_bf16 v[94:97], v[138:141], v[198:201], v[94:97]
	v_mfma_f32_16x16x32_bf16 v[90:93], v[146:149], v[198:201], v[90:93]
	v_mfma_f32_16x16x32_bf16 v[70:73], v[142:145], v[174:177], v[70:73]
	v_mfma_f32_16x16x32_bf16 v[56:59], v[150:153], v[174:177], v[56:59]
	v_mfma_f32_16x16x32_bf16 v[126:129], v[142:145], v[182:185], v[126:129]
	v_mfma_f32_16x16x32_bf16 v[122:125], v[150:153], v[182:185], v[122:125]
	v_mfma_f32_16x16x32_bf16 v[110:113], v[142:145], v[194:197], v[110:113]
	v_mfma_f32_16x16x32_bf16 v[106:109], v[150:153], v[194:197], v[106:109]
	v_mfma_f32_16x16x32_bf16 v[94:97], v[142:145], v[214:217], v[94:97]
	v_mfma_f32_16x16x32_bf16 v[90:93], v[150:153], v[214:217], v[90:93]
	s_setprio 0
	s_setprio 1
	v_mfma_f32_16x16x32_bf16 v[134:137], v[154:157], v[170:173], v[134:137]
	v_mfma_f32_16x16x32_bf16 v[130:133], v[162:165], v[170:173], v[130:133]
	v_mfma_f32_16x16x32_bf16 v[118:121], v[154:157], v[178:181], v[118:121]
	v_mfma_f32_16x16x32_bf16 v[114:117], v[162:165], v[178:181], v[114:117]
	v_mfma_f32_16x16x32_bf16 v[102:105], v[154:157], v[190:193], v[102:105]
	v_mfma_f32_16x16x32_bf16 v[98:101], v[162:165], v[190:193], v[98:101]
	v_mfma_f32_16x16x32_bf16 v[86:89], v[154:157], v[198:201], v[86:89]
	v_mfma_f32_16x16x32_bf16 v[80:83], v[162:165], v[198:201], v[82:85]
	v_mfma_f32_16x16x32_bf16 v[134:137], v[158:161], v[174:177], v[134:137]
	v_mfma_f32_16x16x32_bf16 v[130:133], v[166:169], v[174:177], v[130:133]
	v_mfma_f32_16x16x32_bf16 v[118:121], v[158:161], v[182:185], v[118:121]
	v_mfma_f32_16x16x32_bf16 v[114:117], v[166:169], v[182:185], v[114:117]
	v_mfma_f32_16x16x32_bf16 v[102:105], v[158:161], v[194:197], v[102:105]
	v_mfma_f32_16x16x32_bf16 v[98:101], v[166:169], v[194:197], v[98:101]
	v_mfma_f32_16x16x32_bf16 v[86:89], v[158:161], v[214:217], v[86:89]
	v_mfma_f32_16x16x32_bf16 v[80:83], v[166:169], v[214:217], v[80:83]
	s_setprio 0
	s_barrier
	v_mov_b32_e32 v64, v74
	s_mov_b32 m0, s17
	s_nop 0
	global_load_lds_dwordx4 v64, s[2:3]
	v_mov_b32_e32 v64, v76
	s_mov_b32 m0, s22
	s_nop 0
	global_load_lds_dwordx4 v64, s[2:3]
	v_mov_b32_e32 v64, v75
	s_add_i32 s60, s63, s11
	ds_read_b128 v[170:173], v79 offset:16384
	ds_read_b128 v[174:177], v79 offset:17408
	ds_read_b128 v[178:181], v79 offset:18432
	ds_read_b128 v[182:185], v79 offset:19456
	ds_read_b128 v[190:193], v79 offset:20480
	ds_read_b128 v[194:197], v79 offset:21504
	ds_read_b128 v[198:201], v79 offset:22528
	ds_read_b128 v[214:217], v79 offset:23552
	s_mov_b32 m0, s60
	s_nop 0
	global_load_lds_dwordx4 v64, s[54:55]
	v_mov_b32_e32 v64, v77
	s_add_i32 m0, s60, 0x2000
	s_add_u32 s60, s54, 0x100000
	global_load_lds_dwordx4 v64, s[54:55]
	s_addc_u32 s61, s55, 0
	v_mov_b32_e32 v64, v75
	s_add_i32 s63, s64, s11
	s_mov_b32 m0, s63
	s_nop 0
	global_load_lds_dwordx4 v64, s[60:61]
	v_mov_b32_e32 v64, v77
	s_add_i32 m0, s63, 0x2000
	s_nop 0
	global_load_lds_dwordx4 v64, s[60:61]
	s_waitcnt vmcnt(8)
	s_waitcnt lgkmcnt(0)
	s_barrier
	s_setprio 1
	s_waitcnt lgkmcnt(0)
	v_mfma_f32_16x16x32_bf16 v[66:69], v[138:141], v[170:173], v[66:69]
	v_mfma_f32_16x16x32_bf16 v[60:63], v[146:149], v[170:173], v[60:63]
	v_mfma_f32_16x16x32_bf16 v[44:47], v[138:141], v[178:181], v[44:47]
	v_mfma_f32_16x16x32_bf16 v[40:43], v[146:149], v[178:181], v[40:43]
	v_mfma_f32_16x16x32_bf16 v[28:31], v[138:141], v[190:193], v[28:31]
	v_mfma_f32_16x16x32_bf16 v[24:27], v[146:149], v[190:193], v[24:27]
	v_mfma_f32_16x16x32_bf16 v[12:15], v[138:141], v[198:201], v[12:15]
	v_mfma_f32_16x16x32_bf16 v[8:11], v[146:149], v[198:201], v[8:11]
	v_mfma_f32_16x16x32_bf16 v[66:69], v[142:145], v[174:177], v[66:69]
	v_mfma_f32_16x16x32_bf16 v[60:63], v[150:153], v[174:177], v[60:63]
	v_mfma_f32_16x16x32_bf16 v[44:47], v[142:145], v[182:185], v[44:47]
	v_mfma_f32_16x16x32_bf16 v[40:43], v[150:153], v[182:185], v[40:43]
	v_mfma_f32_16x16x32_bf16 v[28:31], v[142:145], v[194:197], v[28:31]
	v_mfma_f32_16x16x32_bf16 v[24:27], v[150:153], v[194:197], v[24:27]
	v_mfma_f32_16x16x32_bf16 v[12:15], v[142:145], v[214:217], v[12:15]
	v_mfma_f32_16x16x32_bf16 v[8:11], v[150:153], v[214:217], v[8:11]
	s_setprio 0
	s_setprio 1
	v_mfma_f32_16x16x32_bf16 v[52:55], v[154:157], v[170:173], v[52:55]
	v_mfma_f32_16x16x32_bf16 v[48:51], v[162:165], v[170:173], v[48:51]
	v_mfma_f32_16x16x32_bf16 v[36:39], v[154:157], v[178:181], v[36:39]
	v_mfma_f32_16x16x32_bf16 v[32:35], v[162:165], v[178:181], v[32:35]
	v_mfma_f32_16x16x32_bf16 v[20:23], v[154:157], v[190:193], v[20:23]
	v_mfma_f32_16x16x32_bf16 v[16:19], v[162:165], v[190:193], v[16:19]
	v_mfma_f32_16x16x32_bf16 v[4:7], v[154:157], v[198:201], v[4:7]
	v_mfma_f32_16x16x32_bf16 v[0:3], v[162:165], v[198:201], v[0:3]
	v_mfma_f32_16x16x32_bf16 v[52:55], v[158:161], v[174:177], v[52:55]
	v_mfma_f32_16x16x32_bf16 v[48:51], v[166:169], v[174:177], v[48:51]
	v_mfma_f32_16x16x32_bf16 v[36:39], v[158:161], v[182:185], v[36:39]
	v_mfma_f32_16x16x32_bf16 v[32:35], v[166:169], v[182:185], v[32:35]
	v_mfma_f32_16x16x32_bf16 v[20:23], v[158:161], v[194:197], v[20:23]
	v_mfma_f32_16x16x32_bf16 v[16:19], v[166:169], v[194:197], v[16:19]
	v_mfma_f32_16x16x32_bf16 v[4:7], v[158:161], v[214:217], v[4:7]
	v_mfma_f32_16x16x32_bf16 v[0:3], v[166:169], v[214:217], v[0:3]
	s_setprio 0
	s_barrier
	s_add_i32 s63, 0, 0x18000
	v_add_u32_e32 v64, s63, v78
	s_add_i32 s64, 0, 0x1c000
	ds_read_b128 v[138:141], v64
	ds_read_b128 v[142:145], v64 offset:1024
	ds_read_b128 v[146:149], v64 offset:2048
	ds_read_b128 v[150:153], v64 offset:3072
	v_add_u32_e32 v64, s64, v78
	ds_read_b128 v[154:157], v64
	ds_read_b128 v[158:161], v64 offset:1024
	ds_read_b128 v[162:165], v64 offset:2048
	ds_read_b128 v[166:169], v64 offset:3072
	s_add_u32 s60, s2, 0x100000
	v_mov_b32_e32 v64, v74
	s_mov_b32 m0, s49
	ds_read_b128 v[170:173], v79 offset:32768
	ds_read_b128 v[174:177], v79 offset:33792
	ds_read_b128 v[178:181], v79 offset:34816
	ds_read_b128 v[182:185], v79 offset:35840
	ds_read_b128 v[190:193], v79 offset:36864
	ds_read_b128 v[194:197], v79 offset:37888
	ds_read_b128 v[198:201], v79 offset:38912
	ds_read_b128 v[214:217], v79 offset:39936
	s_addc_u32 s61, s3, 0
	s_nop 0
	global_load_lds_dwordx4 v64, s[60:61]
	v_mov_b32_e32 v64, v76
	s_mov_b32 m0, s50
	s_nop 0
	global_load_lds_dwordx4 v64, s[60:61]
	s_waitcnt vmcnt(8)
	s_waitcnt lgkmcnt(0)
	s_barrier
	s_setprio 1
	s_waitcnt lgkmcnt(0)
	v_mfma_f32_16x16x32_bf16 v[70:73], v[138:141], v[170:173], v[70:73]
	v_mfma_f32_16x16x32_bf16 v[56:59], v[146:149], v[170:173], v[56:59]
	v_mfma_f32_16x16x32_bf16 v[126:129], v[138:141], v[178:181], v[126:129]
	v_mfma_f32_16x16x32_bf16 v[122:125], v[146:149], v[178:181], v[122:125]
	v_mfma_f32_16x16x32_bf16 v[110:113], v[138:141], v[190:193], v[110:113]
	v_mfma_f32_16x16x32_bf16 v[106:109], v[146:149], v[190:193], v[106:109]
	v_mfma_f32_16x16x32_bf16 v[94:97], v[138:141], v[198:201], v[94:97]
	v_mfma_f32_16x16x32_bf16 v[90:93], v[146:149], v[198:201], v[90:93]
	v_mfma_f32_16x16x32_bf16 v[70:73], v[142:145], v[174:177], v[70:73]
	v_mfma_f32_16x16x32_bf16 v[56:59], v[150:153], v[174:177], v[56:59]
	v_mfma_f32_16x16x32_bf16 v[126:129], v[142:145], v[182:185], v[126:129]
	v_mfma_f32_16x16x32_bf16 v[122:125], v[150:153], v[182:185], v[122:125]
	v_mfma_f32_16x16x32_bf16 v[110:113], v[142:145], v[194:197], v[110:113]
	v_mfma_f32_16x16x32_bf16 v[106:109], v[150:153], v[194:197], v[106:109]
	v_mfma_f32_16x16x32_bf16 v[94:97], v[142:145], v[214:217], v[94:97]
	v_mfma_f32_16x16x32_bf16 v[90:93], v[150:153], v[214:217], v[90:93]
	s_setprio 0
	s_setprio 1
	v_mfma_f32_16x16x32_bf16 v[134:137], v[154:157], v[170:173], v[134:137]
	v_mfma_f32_16x16x32_bf16 v[130:133], v[162:165], v[170:173], v[130:133]
	v_mfma_f32_16x16x32_bf16 v[118:121], v[154:157], v[178:181], v[118:121]
	v_mfma_f32_16x16x32_bf16 v[114:117], v[162:165], v[178:181], v[114:117]
	v_mfma_f32_16x16x32_bf16 v[102:105], v[154:157], v[190:193], v[102:105]
	v_mfma_f32_16x16x32_bf16 v[98:101], v[162:165], v[190:193], v[98:101]
	v_mfma_f32_16x16x32_bf16 v[84:87], v[154:157], v[198:201], v[86:89]
	v_mfma_f32_16x16x32_bf16 v[80:83], v[162:165], v[198:201], v[80:83]
	v_mfma_f32_16x16x32_bf16 v[134:137], v[158:161], v[174:177], v[134:137]
	v_mfma_f32_16x16x32_bf16 v[130:133], v[166:169], v[174:177], v[130:133]
	v_mfma_f32_16x16x32_bf16 v[118:121], v[158:161], v[182:185], v[118:121]
	v_mfma_f32_16x16x32_bf16 v[114:117], v[166:169], v[182:185], v[114:117]
	v_mfma_f32_16x16x32_bf16 v[102:105], v[158:161], v[194:197], v[102:105]
	v_mfma_f32_16x16x32_bf16 v[98:101], v[166:169], v[194:197], v[98:101]
	v_mfma_f32_16x16x32_bf16 v[86:89], v[158:161], v[214:217], v[84:87]
	v_mfma_f32_16x16x32_bf16 v[82:85], v[166:169], v[214:217], v[80:83]
	s_setprio 0
	s_barrier
	v_mov_b32_e32 v64, v74
	s_mov_b32 m0, s52
	v_lshl_add_u64 v[80:81], s[2:3], 0, v[64:65]
	v_lshl_add_u64 v[80:81], v[80:81], 0, s[24:25]
	v_mov_b32_e32 v64, v76
	global_load_lds_dwordx4 v[80:81], off
	s_mov_b32 m0, s53
	v_lshl_add_u64 v[80:81], s[2:3], 0, v[64:65]
	v_lshl_add_u64 v[80:81], v[80:81], 0, s[24:25]
	global_load_lds_dwordx4 v[80:81], off
	v_mov_b32_e32 v64, v75
	ds_read_b128 v[170:173], v79 offset:49152
	ds_read_b128 v[174:177], v79 offset:50176
	ds_read_b128 v[178:181], v79 offset:51200
	ds_read_b128 v[182:185], v79 offset:52224
	ds_read_b128 v[190:193], v79 offset:53248
	ds_read_b128 v[194:197], v79 offset:54272
	ds_read_b128 v[198:201], v79 offset:55296
	ds_read_b128 v[214:217], v79 offset:56320
	s_add_i32 s60, s63, s11
	v_lshl_add_u64 v[80:81], s[54:55], 0, v[64:65]
	v_lshl_add_u64 v[80:81], v[80:81], 0, s[24:25]
	s_mov_b32 m0, s60
	v_mov_b32_e32 v64, v77
	global_load_lds_dwordx4 v[80:81], off
	s_add_i32 m0, s60, 0x2000
	s_nop 0
	v_lshl_add_u64 v[80:81], s[54:55], 0, v[64:65]
	s_add_u32 s54, s54, 0x100080
	v_lshl_add_u64 v[80:81], v[80:81], 0, s[24:25]
	s_addc_u32 s55, s55, 0
	v_mov_b32_e32 v64, v75
	s_add_i32 s60, s64, s11
	global_load_lds_dwordx4 v[80:81], off
	s_mov_b32 m0, s60
	s_nop 0
	global_load_lds_dwordx4 v64, s[54:55]
	v_mov_b32_e32 v64, v77
	s_add_i32 m0, s60, 0x2000
	s_nop 0
	global_load_lds_dwordx4 v64, s[54:55]
	s_waitcnt vmcnt(8)
	s_waitcnt lgkmcnt(0)
	s_barrier
	s_setprio 1
	s_waitcnt lgkmcnt(0)
	v_mfma_f32_16x16x32_bf16 v[66:69], v[138:141], v[170:173], v[66:69]
	v_mfma_f32_16x16x32_bf16 v[60:63], v[146:149], v[170:173], v[60:63]
	v_mfma_f32_16x16x32_bf16 v[44:47], v[138:141], v[178:181], v[44:47]
	v_mfma_f32_16x16x32_bf16 v[40:43], v[146:149], v[178:181], v[40:43]
	v_mfma_f32_16x16x32_bf16 v[28:31], v[138:141], v[190:193], v[28:31]
	v_mfma_f32_16x16x32_bf16 v[24:27], v[146:149], v[190:193], v[24:27]
	v_mfma_f32_16x16x32_bf16 v[12:15], v[138:141], v[198:201], v[12:15]
	v_mfma_f32_16x16x32_bf16 v[8:11], v[146:149], v[198:201], v[8:11]
	v_mfma_f32_16x16x32_bf16 v[66:69], v[142:145], v[174:177], v[66:69]
	v_mfma_f32_16x16x32_bf16 v[60:63], v[150:153], v[174:177], v[60:63]
	v_mfma_f32_16x16x32_bf16 v[44:47], v[142:145], v[182:185], v[44:47]
	v_mfma_f32_16x16x32_bf16 v[40:43], v[150:153], v[182:185], v[40:43]
	v_mfma_f32_16x16x32_bf16 v[28:31], v[142:145], v[194:197], v[28:31]
	v_mfma_f32_16x16x32_bf16 v[24:27], v[150:153], v[194:197], v[24:27]
	v_mfma_f32_16x16x32_bf16 v[12:15], v[142:145], v[214:217], v[12:15]
	v_mfma_f32_16x16x32_bf16 v[8:11], v[150:153], v[214:217], v[8:11]
	s_setprio 0
	s_setprio 1
	v_mfma_f32_16x16x32_bf16 v[52:55], v[154:157], v[170:173], v[52:55]
	v_mfma_f32_16x16x32_bf16 v[48:51], v[162:165], v[170:173], v[48:51]
	v_mfma_f32_16x16x32_bf16 v[36:39], v[154:157], v[178:181], v[36:39]
	v_mfma_f32_16x16x32_bf16 v[32:35], v[162:165], v[178:181], v[32:35]
	v_mfma_f32_16x16x32_bf16 v[20:23], v[154:157], v[190:193], v[20:23]
	v_mfma_f32_16x16x32_bf16 v[16:19], v[162:165], v[190:193], v[16:19]
	v_mfma_f32_16x16x32_bf16 v[4:7], v[154:157], v[198:201], v[4:7]
	v_mfma_f32_16x16x32_bf16 v[0:3], v[162:165], v[198:201], v[0:3]
	v_mfma_f32_16x16x32_bf16 v[52:55], v[158:161], v[174:177], v[52:55]
	v_mfma_f32_16x16x32_bf16 v[48:51], v[166:169], v[174:177], v[48:51]
	v_mfma_f32_16x16x32_bf16 v[36:39], v[158:161], v[182:185], v[36:39]
	v_mfma_f32_16x16x32_bf16 v[32:35], v[166:169], v[182:185], v[32:35]
	v_mfma_f32_16x16x32_bf16 v[20:23], v[158:161], v[194:197], v[20:23]
	v_mfma_f32_16x16x32_bf16 v[16:19], v[166:169], v[194:197], v[16:19]
	v_mfma_f32_16x16x32_bf16 v[4:7], v[158:161], v[214:217], v[4:7]
	v_mfma_f32_16x16x32_bf16 v[0:3], v[166:169], v[214:217], v[0:3]
	s_setprio 0
	s_barrier
	s_add_i32 s62, s62, 2
	s_add_u32 s92, s92, 0x100
	s_addc_u32 s93, s93, 0
	s_cmp_gt_u32 s62, 61
	s_cbranch_scc0 .LBB0_33
	s_cmp_lt_u32 s48, 4
	s_cbranch_scc0 .LBB0_36
	s_barrier

.LBB0_695:
	s_add_i32 s60, 0, 0x10000
	s_add_i32 s61, 0, 0x14000
	v_add_u32_e32 v64, s60, v134
	ds_read_b128 v[136:139], v64
	ds_read_b128 v[140:143], v64 offset:1024
	ds_read_b128 v[144:147], v64 offset:2048
	ds_read_b128 v[148:151], v64 offset:3072
	v_add_u32_e32 v64, s61, v134
	ds_read_b128 v[152:155], v64
	ds_read_b128 v[156:159], v64 offset:1024
	ds_read_b128 v[160:163], v64 offset:2048
	ds_read_b128 v[164:167], v64 offset:3072
	s_add_u32 s2, s88, 0xfda00080
	s_addc_u32 s3, s89, -1
	s_cmp_lg_u32 s57, 60
	s_cselect_b32 s54, s2, 0
	s_cselect_b32 s55, s3, 0
	s_add_u32 s2, s86, s54
	s_addc_u32 s3, s87, s55
	s_add_u32 s54, s46, s54
	s_addc_u32 s55, s47, s55
	s_add_i32 m0, s17, 0xc000
	v_mov_b32_e32 v64, v130
	s_add_u32 s58, s53, s88
	ds_read_b128 v[168:171], v135
	ds_read_b128 v[172:175], v135 offset:1024
	ds_read_b128 v[176:179], v135 offset:2048
	ds_read_b128 v[180:183], v135 offset:3072
	ds_read_b128 v[184:187], v135 offset:4096
	ds_read_b128 v[190:193], v135 offset:5120
	ds_read_b128 v[194:197], v135 offset:6144
	ds_read_b128 v[198:201], v135 offset:7168
	s_addc_u32 s59, s56, s89
	global_load_lds_dwordx4 v64, s[58:59]
	v_mov_b32_e32 v64, v132
	s_add_i32 m0, s17, 0xe000
	s_nop 0
	global_load_lds_dwordx4 v64, s[58:59]
	s_waitcnt vmcnt(8)
	s_waitcnt lgkmcnt(0)
	s_barrier
	s_setprio 1
	s_waitcnt lgkmcnt(0)
	v_mfma_f32_16x16x32_bf16 v[48:51], v[136:139], v[168:171], v[48:51]
	v_mfma_f32_16x16x32_bf16 v[44:47], v[144:147], v[168:171], v[44:47]
	v_mfma_f32_16x16x32_bf16 v[4:7], v[136:139], v[176:179], v[4:7]
	v_mfma_f32_16x16x32_bf16 v[0:3], v[144:147], v[176:179], v[0:3]
	v_mfma_f32_16x16x32_bf16 v[36:39], v[136:139], v[184:187], v[36:39]
	v_mfma_f32_16x16x32_bf16 v[32:35], v[144:147], v[184:187], v[32:35]
	v_mfma_f32_16x16x32_bf16 v[78:81], v[136:139], v[194:197], v[78:81]
	v_mfma_f32_16x16x32_bf16 v[74:77], v[144:147], v[194:197], v[74:77]
	v_mfma_f32_16x16x32_bf16 v[48:51], v[140:143], v[172:175], v[48:51]
	v_mfma_f32_16x16x32_bf16 v[44:47], v[148:151], v[172:175], v[44:47]
	v_mfma_f32_16x16x32_bf16 v[4:7], v[140:143], v[180:183], v[4:7]
	v_mfma_f32_16x16x32_bf16 v[0:3], v[148:151], v[180:183], v[0:3]
	v_mfma_f32_16x16x32_bf16 v[36:39], v[140:143], v[190:193], v[36:39]
	v_mfma_f32_16x16x32_bf16 v[32:35], v[148:151], v[190:193], v[32:35]
	v_mfma_f32_16x16x32_bf16 v[78:81], v[140:143], v[198:201], v[78:81]
	v_mfma_f32_16x16x32_bf16 v[74:77], v[148:151], v[198:201], v[74:77]
	s_setprio 0
	s_setprio 1
	v_mfma_f32_16x16x32_bf16 v[16:19], v[152:155], v[168:171], v[16:19]
	v_mfma_f32_16x16x32_bf16 v[8:11], v[160:163], v[168:171], v[8:11]
	v_mfma_f32_16x16x32_bf16 v[24:27], v[152:155], v[176:179], v[24:27]
	v_mfma_f32_16x16x32_bf16 v[28:31], v[160:163], v[176:179], v[28:31]
	v_mfma_f32_16x16x32_bf16 v[56:59], v[152:155], v[184:187], v[56:59]
	v_mfma_f32_16x16x32_bf16 v[66:69], v[160:163], v[184:187], v[66:69]
	v_mfma_f32_16x16x32_bf16 v[86:89], v[152:155], v[194:197], v[86:89]
	v_mfma_f32_16x16x32_bf16 v[94:97], v[160:163], v[194:197], v[94:97]
	v_mfma_f32_16x16x32_bf16 v[16:19], v[156:159], v[172:175], v[16:19]
	v_mfma_f32_16x16x32_bf16 v[8:11], v[164:167], v[172:175], v[8:11]
	v_mfma_f32_16x16x32_bf16 v[24:27], v[156:159], v[180:183], v[24:27]
	v_mfma_f32_16x16x32_bf16 v[28:31], v[164:167], v[180:183], v[28:31]
	v_mfma_f32_16x16x32_bf16 v[56:59], v[156:159], v[190:193], v[56:59]
	v_mfma_f32_16x16x32_bf16 v[66:69], v[164:167], v[190:193], v[66:69]
	v_mfma_f32_16x16x32_bf16 v[86:89], v[156:159], v[198:201], v[86:89]
	v_mfma_f32_16x16x32_bf16 v[94:97], v[164:167], v[198:201], v[94:97]
	s_setprio 0
	s_barrier
	v_mov_b32_e32 v64, v130
	s_mov_b32 m0, s17
	s_nop 0
	global_load_lds_dwordx4 v64, s[2:3]
	v_mov_b32_e32 v64, v132
	s_mov_b32 m0, s41
	s_nop 0
	global_load_lds_dwordx4 v64, s[2:3]
	v_mov_b32_e32 v64, v131
	s_add_i32 s58, s60, s11
	ds_read_b128 v[168:171], v135 offset:16384
	ds_read_b128 v[172:175], v135 offset:17408
	ds_read_b128 v[176:179], v135 offset:18432
	ds_read_b128 v[180:183], v135 offset:19456
	ds_read_b128 v[184:187], v135 offset:20480
	ds_read_b128 v[190:193], v135 offset:21504
	ds_read_b128 v[194:197], v135 offset:22528
	ds_read_b128 v[198:201], v135 offset:23552
	s_mov_b32 m0, s58
	s_nop 0
	global_load_lds_dwordx4 v64, s[54:55]
	v_mov_b32_e32 v64, v133
	s_add_i32 m0, s58, 0x2000
	s_add_u32 s58, s54, 0x100000
	global_load_lds_dwordx4 v64, s[54:55]
	s_addc_u32 s59, s55, 0
	v_mov_b32_e32 v64, v131
	s_add_i32 s60, s61, s11
	s_mov_b32 m0, s60
	s_nop 0
	global_load_lds_dwordx4 v64, s[58:59]
	v_mov_b32_e32 v64, v133
	s_add_i32 m0, s60, 0x2000
	s_nop 0
	global_load_lds_dwordx4 v64, s[58:59]
	s_waitcnt vmcnt(8)
	s_waitcnt lgkmcnt(0)
	s_barrier
	s_setprio 1
	s_waitcnt lgkmcnt(0)
	v_mfma_f32_16x16x32_bf16 v[106:109], v[136:139], v[168:171], v[106:109]
	v_mfma_f32_16x16x32_bf16 v[102:105], v[144:147], v[168:171], v[102:105]
	v_mfma_f32_16x16x32_bf16 v[126:129], v[136:139], v[176:179], v[126:129]
	v_mfma_f32_16x16x32_bf16 v[122:125], v[144:147], v[176:179], v[122:125]
	v_mfma_f32_16x16x32_bf16 v[90:93], v[136:139], v[184:187], v[90:93]
	v_mfma_f32_16x16x32_bf16 v[82:85], v[144:147], v[184:187], v[82:85]
	v_mfma_f32_16x16x32_bf16 v[52:55], v[136:139], v[194:197], v[52:55]
	v_mfma_f32_16x16x32_bf16 v[40:43], v[144:147], v[194:197], v[40:43]
	v_mfma_f32_16x16x32_bf16 v[106:109], v[140:143], v[172:175], v[106:109]
	v_mfma_f32_16x16x32_bf16 v[102:105], v[148:151], v[172:175], v[102:105]
	v_mfma_f32_16x16x32_bf16 v[126:129], v[140:143], v[180:183], v[126:129]
	v_mfma_f32_16x16x32_bf16 v[122:125], v[148:151], v[180:183], v[122:125]
	v_mfma_f32_16x16x32_bf16 v[90:93], v[140:143], v[190:193], v[90:93]
	v_mfma_f32_16x16x32_bf16 v[82:85], v[148:151], v[190:193], v[82:85]
	v_mfma_f32_16x16x32_bf16 v[52:55], v[140:143], v[198:201], v[52:55]
	v_mfma_f32_16x16x32_bf16 v[40:43], v[148:151], v[198:201], v[40:43]
	s_setprio 0
	s_setprio 1
	v_mfma_f32_16x16x32_bf16 v[114:117], v[152:155], v[168:171], v[114:117]
	v_mfma_f32_16x16x32_bf16 v[118:121], v[160:163], v[168:171], v[118:121]
	v_mfma_f32_16x16x32_bf16 v[110:113], v[152:155], v[176:179], v[110:113]
	v_mfma_f32_16x16x32_bf16 v[98:101], v[160:163], v[176:179], v[98:101]
	v_mfma_f32_16x16x32_bf16 v[70:73], v[152:155], v[184:187], v[70:73]
	v_mfma_f32_16x16x32_bf16 v[60:63], v[160:163], v[184:187], v[60:63]
	v_mfma_f32_16x16x32_bf16 v[20:23], v[152:155], v[194:197], v[20:23]
	v_mfma_f32_16x16x32_bf16 v[12:15], v[160:163], v[194:197], v[12:15]
	v_mfma_f32_16x16x32_bf16 v[114:117], v[156:159], v[172:175], v[114:117]
	v_mfma_f32_16x16x32_bf16 v[118:121], v[164:167], v[172:175], v[118:121]
	v_mfma_f32_16x16x32_bf16 v[110:113], v[156:159], v[180:183], v[110:113]
	v_mfma_f32_16x16x32_bf16 v[98:101], v[164:167], v[180:183], v[98:101]
	v_mfma_f32_16x16x32_bf16 v[70:73], v[156:159], v[190:193], v[70:73]
	v_mfma_f32_16x16x32_bf16 v[60:63], v[164:167], v[190:193], v[60:63]
	v_mfma_f32_16x16x32_bf16 v[20:23], v[156:159], v[198:201], v[20:23]
	v_mfma_f32_16x16x32_bf16 v[12:15], v[164:167], v[198:201], v[12:15]
	s_setprio 0
	s_barrier
	s_add_i32 s60, 0, 0x18000
	v_add_u32_e32 v64, s60, v134
	s_add_i32 s61, 0, 0x1c000
	ds_read_b128 v[136:139], v64
	ds_read_b128 v[140:143], v64 offset:1024
	ds_read_b128 v[144:147], v64 offset:2048
	ds_read_b128 v[148:151], v64 offset:3072
	v_add_u32_e32 v64, s61, v134
	ds_read_b128 v[152:155], v64
	ds_read_b128 v[156:159], v64 offset:1024
	ds_read_b128 v[160:163], v64 offset:2048
	ds_read_b128 v[164:167], v64 offset:3072
	s_add_u32 s58, s2, 0x100000
	v_mov_b32_e32 v64, v130
	s_mov_b32 m0, s49
	ds_read_b128 v[168:171], v135 offset:32768
	ds_read_b128 v[172:175], v135 offset:33792
	ds_read_b128 v[176:179], v135 offset:34816
	ds_read_b128 v[180:183], v135 offset:35840
	ds_read_b128 v[184:187], v135 offset:36864
	ds_read_b128 v[190:193], v135 offset:37888
	ds_read_b128 v[194:197], v135 offset:38912
	ds_read_b128 v[198:201], v135 offset:39936
	s_addc_u32 s59, s3, 0
	s_nop 0
	global_load_lds_dwordx4 v64, s[58:59]
	v_mov_b32_e32 v64, v132
	s_mov_b32 m0, s50
	s_nop 0
	global_load_lds_dwordx4 v64, s[58:59]
	s_waitcnt vmcnt(8)
	s_waitcnt lgkmcnt(0)
	s_barrier
	s_setprio 1
	s_waitcnt lgkmcnt(0)
	v_mfma_f32_16x16x32_bf16 v[48:51], v[136:139], v[168:171], v[48:51]
	v_mfma_f32_16x16x32_bf16 v[44:47], v[144:147], v[168:171], v[44:47]
	v_mfma_f32_16x16x32_bf16 v[4:7], v[136:139], v[176:179], v[4:7]
	v_mfma_f32_16x16x32_bf16 v[0:3], v[144:147], v[176:179], v[0:3]
	v_mfma_f32_16x16x32_bf16 v[36:39], v[136:139], v[184:187], v[36:39]
	v_mfma_f32_16x16x32_bf16 v[32:35], v[144:147], v[184:187], v[32:35]
	v_mfma_f32_16x16x32_bf16 v[78:81], v[136:139], v[194:197], v[78:81]
	v_mfma_f32_16x16x32_bf16 v[74:77], v[144:147], v[194:197], v[74:77]
	v_mfma_f32_16x16x32_bf16 v[48:51], v[140:143], v[172:175], v[48:51]
	v_mfma_f32_16x16x32_bf16 v[44:47], v[148:151], v[172:175], v[44:47]
	v_mfma_f32_16x16x32_bf16 v[4:7], v[140:143], v[180:183], v[4:7]
	v_mfma_f32_16x16x32_bf16 v[0:3], v[148:151], v[180:183], v[0:3]
	v_mfma_f32_16x16x32_bf16 v[36:39], v[140:143], v[190:193], v[36:39]
	v_mfma_f32_16x16x32_bf16 v[32:35], v[148:151], v[190:193], v[32:35]
	v_mfma_f32_16x16x32_bf16 v[78:81], v[140:143], v[198:201], v[78:81]
	v_mfma_f32_16x16x32_bf16 v[74:77], v[148:151], v[198:201], v[74:77]
	s_setprio 0
	s_setprio 1
	v_mfma_f32_16x16x32_bf16 v[16:19], v[152:155], v[168:171], v[16:19]
	v_mfma_f32_16x16x32_bf16 v[8:11], v[160:163], v[168:171], v[8:11]
	v_mfma_f32_16x16x32_bf16 v[24:27], v[152:155], v[176:179], v[24:27]
	v_mfma_f32_16x16x32_bf16 v[28:31], v[160:163], v[176:179], v[28:31]
	v_mfma_f32_16x16x32_bf16 v[56:59], v[152:155], v[184:187], v[56:59]
	v_mfma_f32_16x16x32_bf16 v[66:69], v[160:163], v[184:187], v[66:69]
	v_mfma_f32_16x16x32_bf16 v[86:89], v[152:155], v[194:197], v[86:89]
	v_mfma_f32_16x16x32_bf16 v[94:97], v[160:163], v[194:197], v[94:97]
	v_mfma_f32_16x16x32_bf16 v[16:19], v[156:159], v[172:175], v[16:19]
	v_mfma_f32_16x16x32_bf16 v[8:11], v[164:167], v[172:175], v[8:11]
	v_mfma_f32_16x16x32_bf16 v[24:27], v[156:159], v[180:183], v[24:27]
	v_mfma_f32_16x16x32_bf16 v[28:31], v[164:167], v[180:183], v[28:31]
	v_mfma_f32_16x16x32_bf16 v[56:59], v[156:159], v[190:193], v[56:59]
	v_mfma_f32_16x16x32_bf16 v[66:69], v[164:167], v[190:193], v[66:69]
	v_mfma_f32_16x16x32_bf16 v[86:89], v[156:159], v[198:201], v[86:89]
	v_mfma_f32_16x16x32_bf16 v[94:97], v[164:167], v[198:201], v[94:97]
	s_setprio 0
	s_barrier
	v_mov_b32_e32 v64, v130
	s_mov_b32 m0, s51
	v_lshl_add_u64 v[214:215], s[2:3], 0, v[64:65]
	v_lshl_add_u64 v[214:215], v[214:215], 0, s[24:25]
	v_mov_b32_e32 v64, v132
	global_load_lds_dwordx4 v[214:215], off
	s_mov_b32 m0, s52
	v_lshl_add_u64 v[214:215], s[2:3], 0, v[64:65]
	v_lshl_add_u64 v[214:215], v[214:215], 0, s[24:25]
	global_load_lds_dwordx4 v[214:215], off
	v_mov_b32_e32 v64, v131
	ds_read_b128 v[168:171], v135 offset:49152
	ds_read_b128 v[172:175], v135 offset:50176
	ds_read_b128 v[176:179], v135 offset:51200
	ds_read_b128 v[180:183], v135 offset:52224
	ds_read_b128 v[184:187], v135 offset:53248
	ds_read_b128 v[190:193], v135 offset:54272
	ds_read_b128 v[194:197], v135 offset:55296
	ds_read_b128 v[198:201], v135 offset:56320
	s_add_i32 s58, s60, s11
	v_lshl_add_u64 v[214:215], s[54:55], 0, v[64:65]
	v_lshl_add_u64 v[214:215], v[214:215], 0, s[24:25]
	s_mov_b32 m0, s58
	v_mov_b32_e32 v64, v133
	global_load_lds_dwordx4 v[214:215], off
	s_add_i32 m0, s58, 0x2000
	s_nop 0
	v_lshl_add_u64 v[214:215], s[54:55], 0, v[64:65]
	s_add_u32 s54, s54, 0x100080
	v_lshl_add_u64 v[214:215], v[214:215], 0, s[24:25]
	s_addc_u32 s55, s55, 0
	v_mov_b32_e32 v64, v131
	s_add_i32 s58, s61, s11
	global_load_lds_dwordx4 v[214:215], off
	s_mov_b32 m0, s58
	s_nop 0
	global_load_lds_dwordx4 v64, s[54:55]
	v_mov_b32_e32 v64, v133
	s_add_i32 m0, s58, 0x2000
	s_nop 0
	global_load_lds_dwordx4 v64, s[54:55]
	s_waitcnt vmcnt(8)
	s_waitcnt lgkmcnt(0)
	s_barrier
	s_setprio 1
	s_waitcnt lgkmcnt(0)
	v_mfma_f32_16x16x32_bf16 v[106:109], v[136:139], v[168:171], v[106:109]
	v_mfma_f32_16x16x32_bf16 v[102:105], v[144:147], v[168:171], v[102:105]
	v_mfma_f32_16x16x32_bf16 v[126:129], v[136:139], v[176:179], v[126:129]
	v_mfma_f32_16x16x32_bf16 v[122:125], v[144:147], v[176:179], v[122:125]
	v_mfma_f32_16x16x32_bf16 v[90:93], v[136:139], v[184:187], v[90:93]
	v_mfma_f32_16x16x32_bf16 v[82:85], v[144:147], v[184:187], v[82:85]
	v_mfma_f32_16x16x32_bf16 v[52:55], v[136:139], v[194:197], v[52:55]
	v_mfma_f32_16x16x32_bf16 v[40:43], v[144:147], v[194:197], v[40:43]
	v_mfma_f32_16x16x32_bf16 v[106:109], v[140:143], v[172:175], v[106:109]
	v_mfma_f32_16x16x32_bf16 v[102:105], v[148:151], v[172:175], v[102:105]
	v_mfma_f32_16x16x32_bf16 v[126:129], v[140:143], v[180:183], v[126:129]
	v_mfma_f32_16x16x32_bf16 v[122:125], v[148:151], v[180:183], v[122:125]
	v_mfma_f32_16x16x32_bf16 v[90:93], v[140:143], v[190:193], v[90:93]
	v_mfma_f32_16x16x32_bf16 v[82:85], v[148:151], v[190:193], v[82:85]
	v_mfma_f32_16x16x32_bf16 v[52:55], v[140:143], v[198:201], v[52:55]
	v_mfma_f32_16x16x32_bf16 v[40:43], v[148:151], v[198:201], v[40:43]
	s_setprio 0
	s_setprio 1
	v_mfma_f32_16x16x32_bf16 v[114:117], v[152:155], v[168:171], v[114:117]
	v_mfma_f32_16x16x32_bf16 v[118:121], v[160:163], v[168:171], v[118:121]
	v_mfma_f32_16x16x32_bf16 v[110:113], v[152:155], v[176:179], v[110:113]
	v_mfma_f32_16x16x32_bf16 v[98:101], v[160:163], v[176:179], v[98:101]
	v_mfma_f32_16x16x32_bf16 v[70:73], v[152:155], v[184:187], v[70:73]
	v_mfma_f32_16x16x32_bf16 v[60:63], v[160:163], v[184:187], v[60:63]
	v_mfma_f32_16x16x32_bf16 v[20:23], v[152:155], v[194:197], v[20:23]
	v_mfma_f32_16x16x32_bf16 v[12:15], v[160:163], v[194:197], v[12:15]
	v_mfma_f32_16x16x32_bf16 v[114:117], v[156:159], v[172:175], v[114:117]
	v_mfma_f32_16x16x32_bf16 v[118:121], v[164:167], v[172:175], v[118:121]
	v_mfma_f32_16x16x32_bf16 v[110:113], v[156:159], v[180:183], v[110:113]
	v_mfma_f32_16x16x32_bf16 v[98:101], v[164:167], v[180:183], v[98:101]
	v_mfma_f32_16x16x32_bf16 v[70:73], v[156:159], v[190:193], v[70:73]
	v_mfma_f32_16x16x32_bf16 v[60:63], v[164:167], v[190:193], v[60:63]
	v_mfma_f32_16x16x32_bf16 v[20:23], v[156:159], v[198:201], v[20:23]
	v_mfma_f32_16x16x32_bf16 v[12:15], v[164:167], v[198:201], v[12:15]
	s_setprio 0
	s_barrier
	s_add_i32 s57, s57, 2
	s_add_u32 s88, s88, 0x100
	s_addc_u32 s89, s89, 0
	s_cmp_gt_u32 s57, 61
	s_cbranch_scc0 .LBB0_695
	s_cmp_lt_u32 s48, 4
	s_cbranch_scc0 .LBB0_698
	s_barrier
